# adds: dilated-attention items issue the key-norm bound and first K/V tile loads right behind the Q loads (address slice duplicated into dead registers)
# baseline (speedup 1.0000x reference)
; template <int TYPE>
; DI void attn_item(const Params& p, int layer, int head, int qt, int dil, int res, int chunk, char* smem) {
;     ...
;   const int Q0 = qt * 256;
;   const int wq0 = Q0 + 32 * wid;
;   const int Uq = wq0 + ql;
;   const size_t tq = (size_t)Uq * dil + res;
;   bf16x8 qf[4];
; #pragma unroll
;   for (int ks = 0; ks < 4; ++ks) qf[ks] = *(const bf16x8*)(proj + tq * DIN + qcol + ks * 16 + h * 8);
;   char* sK = smem;
;   char* sV = smem + 8192;
;   volatile int* sflag = (volatile int*)(smem + FLG + 32);
;   volatile float* dred = (volatile float*)(smem + FLG + 96);
;   float slope = 0.f;
;   if (TYPE == 0) slope = exp2f(-8.f * (float)(head + 1) / 6.f) * (float)dil * LOG2E;
;   if (TYPE == 1) slope = exp2f(-2.f * (float)(head + 1)) * LOG2E;
;   const int wlim = (TYPE == 0) ? 128 : 0x3fffffff;
;   int kt_hi = (Q0 >> 6) + 3;
;   int kt_lo = 0;
;   float cref = 0.f;
;   if (TYPE == 0) {
;     kt_lo = (Q0 >> 6) - 2;
;     if (kt_lo < 0) kt_lo = 0;
;     const float* kma = (const float*)(p.ws + OFF_KMAX) + layer * 32;
;     const float km2 = kma[2 * head] + kma[2 * head + 1];
;     float qn2 = dot8(qf[0], qf[0]) + dot8(qf[1], qf[1]) + dot8(qf[2], qf[2]) + dot8(qf[3], qf[3]);
;     qn2 += __shfl_xor(qn2, 32);
;     const float R = sqrtf(qn2 * km2) * 1.01f + 0.01f;
;     cref = fmaxf(0.f, R - 60.f);
; DI void attn_phase(const Params& p, int layer, char* smem) {
;     ...
;   for (;;) {
;     __syncthreads();
;     if (threadIdx.x == 0) *s_item = atomicAdd(counter + 2, 1);
;     __syncthreads();
;     const int j = *s_item;
;     if (j >= 1152) break;
;     const int head = j % 6, branch = (j / 6) % 3, n = j / 18;
;     const int dil = branch == 0 ? 1 : branch == 1 ? 4 : 16;
;     attn_item<0>(p, layer, head, n / dil, dil, n % dil, branch, smem);
.LBB0_252:
	s_or_b64 exec, exec, s[0:1]
	s_waitcnt lgkmcnt(0)
	s_barrier
	ds_read_b32 v0, v76
	s_waitcnt lgkmcnt(0)
	s_mov_b64 s[0:1], -1
	s_waitcnt lgkmcnt(0)
	v_cmp_gt_i32_e32 vcc, s33, v0
	s_and_saveexec_b64 s[62:63], vcc
	s_cbranch_execz .LBB0_247
	v_mul_hi_i32 v1, v0, s68
	v_lshrrev_b32_e32 v2, 31, v1
	v_add_u32_e32 v1, v1, v2
	v_mul_lo_u32 v2, v1, 6
	v_sub_u32_e32 v78, v0, v2
	v_mul_hi_i32 v2, v1, s69
	v_lshrrev_b32_e32 v3, 31, v2
	v_add_u32_e32 v2, v2, v3
	v_lshl_add_u32 v2, v2, 1, v2
	v_sub_u32_e32 v80, v1, v2
	v_cmp_eq_u32_e32 vcc, 1, v80
	v_cmp_eq_u32_e64 s[0:1], 0, v80
	v_mul_hi_i32 v0, v0, s70
	v_cndmask_b32_e64 v2, 16, 4, vcc
	v_cndmask_b32_e64 v2, v2, 1, s[0:1]
	v_cvt_f32_ubyte0_e32 v37, v2
	v_rcp_iflag_f32_e32 v3, v37
	v_lshrrev_b32_e32 v1, 31, v0
	v_ashrrev_i32_e32 v0, 2, v0
	v_add_u32_e32 v0, v0, v1
	v_mul_f32_e32 v1, 0x4f7ffffe, v3
	v_cvt_u32_f32_e32 v1, v1
	v_sub_u32_e32 v4, 0, v2
	v_sub_u32_e32 v3, 0, v0
	v_max_i32_e32 v3, v0, v3
	v_mul_lo_u32 v4, v4, v1
	v_mul_hi_u32 v4, v1, v4
	v_add_u32_e32 v1, v1, v4
	v_mul_hi_u32 v1, v3, v1
	v_mul_lo_u32 v4, v1, v2
	v_sub_u32_e32 v3, v3, v4
	v_add_u32_e32 v4, 1, v1
	v_cmp_ge_u32_e64 s[2:3], v3, v2
	v_ashrrev_i32_e32 v32, 31, v0
	v_mov_b32_e32 v39, v158
	v_cndmask_b32_e64 v1, v1, v4, s[2:3]
	v_sub_u32_e32 v4, v3, v2
	v_cndmask_b32_e64 v3, v3, v4, s[2:3]
	v_add_u32_e32 v4, 1, v1
	v_cmp_ge_u32_e64 s[2:3], v3, v2
	v_lshlrev_b32_e32 v84, 6, v78
	v_ashrrev_i32_e32 v38, 6, v39
	v_cndmask_b32_e64 v1, v1, v4, s[2:3]
	v_xor_b32_e32 v33, v1, v32
	v_sub_u32_e32 v3, v33, v32
	v_lshlrev_b32_e32 v35, 5, v38
	v_mul_lo_u32 v1, v3, v2
	v_and_b32_e32 v34, 31, v39
	v_lshl_add_u32 v40, v3, 8, v35
	v_sub_u32_e32 v86, v0, v1
	v_or_b32_e32 v0, v40, v34
	v_cndmask_b32_e64 v2, 4, 2, vcc
	v_ashrrev_i32_e32 v1, 31, v0
	v_cndmask_b32_e64 v79, v2, 0, s[0:1]
	v_lshlrev_b64 v[0:1], v79, v[0:1]
	v_ashrrev_i32_e32 v87, 31, v86
	v_lshl_add_u64 v[82:83], v[0:1], 0, v[86:87]
	v_mov_b64_e32 v[0:1], s[12:13]
	v_mad_u64_u32 v[0:1], s[0:1], v82, s71, v[0:1]
	v_bfe_u32 v36, v39, 5, 1
	v_mad_i32_i24 v1, v83, s71, v1
	v_ashrrev_i32_e32 v85, 31, v84
	v_lshl_add_u64 v[0:1], v[84:85], 1, v[0:1]
	v_lshlrev_b32_e32 v72, 4, v36
	v_lshl_add_u64 v[0:1], v[0:1], 0, v[72:73]
	global_load_dwordx4 v[48:51], v[0:1], off
	global_load_dwordx4 v[52:55], v[0:1], off offset:32
	global_load_dwordx4 v[56:59], v[0:1], off offset:64
	global_load_dwordx4 v[60:63], v[0:1], off offset:96
	v_mov_b32_e32 v171, v3
	v_mov_b32_e32 v195, v73
	v_lshlrev_b32_e32 v168, 2, v171
	v_or_b32_e32 v197, 3, v168
	v_and_b32_e32 v196, 63, v39
	v_lshlrev_b32_e32 v168, 1, v78
	v_ashrrev_i32_e32 v169, 31, v168
	v_lshl_add_u64 v[168:169], v[168:169], 2, s[30:31]
	global_load_dwordx2 v[168:169], v[168:169], off
	v_add_u32_e32 v194, 0x180, v84
	v_ashrrev_i32_e32 v198, 3, v39
	v_lshlrev_b32_e32 v174, 4, v39
	v_lshlrev_b32_e32 v180, 6, v197
	v_mov_b32_e32 v175, v195
	v_lshlrev_b64 v[178:179], 1, v[194:195]
	v_and_b32_e32 v194, 0x70, v174
	v_or_b32_e32 v174, v196, v180
	v_add_u32_e32 v180, v198, v180
	v_lshlrev_b64 v[174:175], v79, v[174:175]
	v_ashrrev_i32_e32 v181, 31, v180
	v_mov_b64_e32 v[176:177], s[12:13]
	v_lshl_add_u64 v[174:175], v[174:175], 0, v[86:87]
	v_lshlrev_b64 v[180:181], v79, v[180:181]
	v_add_u32_e32 v170, 0x300, v84
	v_mov_b32_e32 v171, v195
	v_lshlrev_b32_e32 v172, 3, v38
	v_mad_u64_u32 v[182:183], s[98:99], v174, s71, v[176:177]
	v_lshl_add_u64 v[180:181], v[180:181], 0, v[86:87]
	v_ashrrev_i32_e32 v173, 31, v172
	v_lshlrev_b64 v[170:171], 1, v[170:171]
	v_mad_i32_i24 v183, v175, s71, v183
	v_mad_u64_u32 v[174:175], s[98:99], v180, s71, v[176:177]
	v_lshlrev_b64 v[184:185], 1, v[172:173]
	v_lshl_add_u64 v[170:171], v[182:183], 0, v[170:171]
	v_mad_i32_i24 v175, v181, s71, v175
	v_lshl_add_u64 v[170:171], v[170:171], 0, v[184:185]
	v_lshl_add_u64 v[174:175], v[174:175], 0, v[178:179]
	global_load_dwordx4 v[186:189], v[170:171], off
	v_lshl_add_u64 v[170:171], v[174:175], 0, v[194:195]
	global_load_dwordx4 v[190:193], v[170:171], off
	v_lshlrev_b32_e32 v0, 2, v3
	v_cmp_lt_i32_e32 vcc, v159, v165
	v_max_i32_e32 v1, 2, v0
	v_or_b32_e32 v99, 3, v0
	v_add_u32_e32 v100, -2, v1
	v_and_b32_e32 v75, 63, v39
	v_lshlrev_b32_e32 v72, 2, v36
	s_waitcnt vmcnt(6)
	v_and_b32_e32 v3, 0xffff0000, v48
	s_waitcnt vmcnt(5)
	v_and_b32_e32 v11, 0xffff0000, v52
	v_lshlrev_b32_e32 v2, 16, v48
	v_lshlrev_b32_e32 v10, 16, v52
	v_mul_f32_e32 v3, v3, v3
	v_mul_f32_e32 v11, v11, v11
	v_lshlrev_b32_e32 v4, 16, v49
	v_lshlrev_b32_e32 v12, 16, v53
	v_fmac_f32_e32 v3, v2, v2
	v_fmac_f32_e32 v11, v10, v10
	v_and_b32_e32 v5, 0xffff0000, v49
	v_and_b32_e32 v13, 0xffff0000, v53
	v_fmac_f32_e32 v3, v4, v4
	v_fmac_f32_e32 v11, v12, v12
	v_lshlrev_b32_e32 v6, 16, v50
	v_lshlrev_b32_e32 v14, 16, v54
	s_waitcnt vmcnt(4)
	v_and_b32_e32 v19, 0xffff0000, v56
	v_fmac_f32_e32 v3, v5, v5
	v_fmac_f32_e32 v11, v13, v13
	v_and_b32_e32 v7, 0xffff0000, v50
	v_and_b32_e32 v15, 0xffff0000, v54
	v_lshlrev_b32_e32 v18, 16, v56
	s_waitcnt vmcnt(3)
	v_and_b32_e32 v27, 0xffff0000, v60
	v_mul_f32_e32 v19, v19, v19
	v_fmac_f32_e32 v3, v6, v6
	v_fmac_f32_e32 v11, v14, v14
	v_lshlrev_b32_e32 v8, 16, v51
	v_lshlrev_b32_e32 v16, 16, v55
	v_lshlrev_b32_e32 v20, 16, v57
	v_lshlrev_b32_e32 v26, 16, v60
	v_mul_f32_e32 v27, v27, v27
	v_fmac_f32_e32 v19, v18, v18
	v_fmac_f32_e32 v3, v7, v7
	v_fmac_f32_e32 v11, v15, v15
	v_and_b32_e32 v9, 0xffff0000, v51
	v_and_b32_e32 v17, 0xffff0000, v55
	v_and_b32_e32 v21, 0xffff0000, v57
	v_lshlrev_b32_e32 v28, 16, v61
	v_fmac_f32_e32 v27, v26, v26
	v_fmac_f32_e32 v19, v20, v20
	v_fmac_f32_e32 v3, v8, v8
	v_fmac_f32_e32 v11, v16, v16
	v_lshlrev_b32_e32 v22, 16, v58
	v_and_b32_e32 v29, 0xffff0000, v61
	v_fmac_f32_e32 v27, v28, v28
	v_fmac_f32_e32 v19, v21, v21
	v_fmac_f32_e32 v3, v9, v9
	v_fmac_f32_e32 v11, v17, v17
	v_and_b32_e32 v23, 0xffff0000, v58
	v_fmac_f32_e32 v19, v22, v22
	v_add_f32_e32 v2, v3, v11
	v_fmac_f32_e32 v27, v29, v29
	v_lshlrev_b32_e32 v3, 16, v62
	v_lshlrev_b32_e32 v24, 16, v59
	v_fmac_f32_e32 v19, v23, v23
	v_fmac_f32_e32 v27, v3, v3
	v_and_b32_e32 v3, 0xffff0000, v62
	v_and_b32_e32 v25, 0xffff0000, v59
	v_fmac_f32_e32 v19, v24, v24
	v_fmac_f32_e32 v27, v3, v3
	v_lshlrev_b32_e32 v3, 16, v63
	v_fmac_f32_e32 v19, v25, v25
	v_fmac_f32_e32 v27, v3, v3
	v_and_b32_e32 v3, 0xffff0000, v63
	v_add_f32_e32 v2, v2, v19
	v_fmac_f32_e32 v27, v3, v3
	v_add_f32_e32 v41, v2, v27
	v_cndmask_b32_e32 v2, v164, v159, vcc
	v_lshlrev_b32_e32 v81, 2, v2
	ds_bpermute_b32 v42, v81, v41
	v_cmp_ge_i32_e32 vcc, v99, v100
	s_and_saveexec_b64 s[0:1], vcc
	s_xor_b64 s[64:65], exec, s[0:1]
	s_cbranch_execz .LBB0_261
; template <int TYPE>
; DI void attn_item(const Params& p, int layer, int head, int qt, int dil, int res, int chunk, char* smem) {
;     ...
;   if (TYPE == 0) slope = exp2f(-8.f * (float)(head + 1) / 6.f) * (float)dil * LOG2E;
;   if (TYPE == 1) slope = exp2f(-2.f * (float)(head + 1)) * LOG2E;
;   const int wlim = (TYPE == 0) ? 128 : 0x3fffffff;
;   int kt_hi = (Q0 >> 6) + 3;
;   int kt_lo = 0;
;   float cref = 0.f;
;   if (TYPE == 0) {
;     kt_lo = (Q0 >> 6) - 2;
;     if (kt_lo < 0) kt_lo = 0;
;     const float* kma = (const float*)(p.ws + OFF_KMAX) + layer * 32;
;     const float km2 = kma[2 * head] + kma[2 * head + 1];
;     float qn2 = dot8(qf[0], qf[0]) + dot8(qf[1], qf[1]) + dot8(qf[2], qf[2]) + dot8(qf[3], qf[3]);
;     qn2 += __shfl_xor(qn2, 32);
;     const float R = sqrtf(qn2 * km2) * 1.01f + 0.01f;
;     cref = fmaxf(0.f, R - 60.f);
;     ...
;   float l1 = 0.f, l2 = 0.f, carry = 0.f;
;   f32x16 O1a, O1b, O2a, O2b;
; #pragma unroll
;   for (int i = 0; i < 16; ++i) { O1a[i] = 0.f; O1b[i] = 0.f; O2a[i] = 0.f; O2b[i] = 0.f; }
;   bf16x8 Tm0, Tm1;
;   if (TYPE == 2) {
; #pragma unroll
;     for (int jj = 0; jj < 8; ++jj) {
;       int k0 = 8 * (jj >> 2) + 4 * h + (jj & 3);
;       Tm0[jj] = (k0 > ql) ? (short)0x3F80 : (short)0;
;       Tm1[jj] = (16 + k0 > ql) ? (short)0x3F80 : (short)0;
;     }
;     if (tid < 8) sflag[tid] = 0;
;   }
;   const int kkey0 = tid >> 3, kchunk = tid & 7;
;   const int vkey = tid & 63, vdc0 = tid >> 6;
;   const int vk5 = vkey & 31;
;   const int vpos = (vkey & 32) | (vk5 & 0x13) | ((vk5 & 8) >> 1) | ((vk5 & 4) << 1);
;   uint4 kreg0, vreg0;
;     ...
;   ATT_PREFETCH((kt_hi >= kt_lo) ? kt_hi : 0);
	v_lshlrev_b32_e32 v0, 1, v78
	v_ashrrev_i32_e32 v1, 31, v0
	v_lshl_add_u64 v[0:1], v[0:1], 2, s[30:31]
	s_waitcnt vmcnt(2)
	v_mov_b64_e32 v[0:1], v[168:169]
	v_add_u32_e32 v72, 0x180, v84
	v_ashrrev_i32_e32 v101, 3, v39
	v_lshlrev_b32_e32 v6, 4, v39
	v_lshlrev_b32_e32 v12, 6, v99
	v_mov_b32_e32 v7, v73
	v_lshlrev_b32_e32 v13, 1, v39
	v_and_b32_e32 v14, 48, v39
	v_lshlrev_b64 v[10:11], 1, v[72:73]
	v_and_b32_e32 v72, 0x70, v6
	v_or_b32_e32 v6, v75, v12
	v_add_u32_e32 v12, v101, v12
	s_waitcnt lgkmcnt(0)
	v_add_f32_e32 v20, v41, v42
	v_and_or_b32 v23, v13, 8, v14
	v_and_b32_e32 v41, 6, v13
	v_lshlrev_b64 v[6:7], v79, v[6:7]
	v_ashrrev_i32_e32 v13, 31, v12
	v_mov_b64_e32 v[8:9], s[12:13]
	v_lshl_add_u64 v[14:15], s[12:13], 0, v[10:11]
	v_lshl_add_u64 v[6:7], v[6:7], 0, v[86:87]
	v_lshlrev_b64 v[12:13], v79, v[12:13]
	v_add_u32_e32 v5, 1, v78
	v_add_u32_e32 v2, 0x300, v84
	v_mov_b32_e32 v3, v73
	v_lshlrev_b32_e32 v4, 3, v38
	v_lshl_add_u64 v[88:89], v[14:15], 0, v[72:73]
	v_mad_u64_u32 v[14:15], s[0:1], v6, s71, v[8:9]
	v_lshl_add_u64 v[12:13], v[12:13], 0, v[86:87]
	v_cvt_f32_i32_e32 v22, v5
	v_ashrrev_i32_e32 v5, 31, v4
	v_lshlrev_b64 v[2:3], 1, v[2:3]
	v_mad_i32_i24 v15, v7, s71, v15
	v_mad_u64_u32 v[6:7], s[0:1], v12, s71, v[8:9]
	v_lshl_add_u64 v[16:17], s[12:13], 0, v[2:3]
	v_lshlrev_b64 v[18:19], 1, v[4:5]
	v_lshl_add_u64 v[2:3], v[14:15], 0, v[2:3]
	v_mad_i32_i24 v7, v13, s71, v7
	v_lshl_add_u64 v[2:3], v[2:3], 0, v[18:19]
	v_lshl_add_u64 v[6:7], v[6:7], 0, v[10:11]
	s_waitcnt vmcnt(0)
	v_mov_b64_e32 v[64:65], v[186:187]
	v_mov_b64_e32 v[66:67], v[188:189]
	v_lshl_add_u64 v[2:3], v[6:7], 0, v[72:73]
	v_mov_b64_e32 v[68:69], v[190:191]
	v_mov_b64_e32 v[70:71], v[192:193]
	v_lshl_add_u64 v[90:91], v[16:17], 0, v[18:19]
	v_mul_f32_e32 v16, 0xc1000000, v22
	v_div_scale_f32 v8, s[0:1], s72, s72, v16
	v_rcp_f32_e32 v12, v8
	v_div_scale_f32 v9, vcc, v16, s72, v16
	v_lshrrev_b32_e32 v23, 3, v23
	v_fma_f32 v2, -v8, v12, 1.0
	v_fmac_f32_e32 v12, v2, v12
	v_mul_f32_e32 v2, v9, v12
	v_fma_f32 v3, -v8, v2, v9
	v_fmac_f32_e32 v2, v3, v12
	v_fma_f32 v3, -v8, v2, v9
	v_div_fmas_f32 v2, v3, v12, v2
	v_div_fixup_f32 v2, v2, s72, v16
	v_cmp_gt_f32_e32 vcc, s73, v2
	v_and_b32_e32 v21, 8, v39
	v_lshrrev_b32_e32 v24, 1, v101
	v_cndmask_b32_e32 v3, 0, v96, vcc
	v_add_f32_e32 v2, v2, v3
	v_cndmask_b32_e32 v3, 0, v97, vcc
	v_exp_f32_e32 v2, v2
	v_lshlrev_b32_e32 v72, 2, v36
	v_add_u32_e32 v13, v35, v34
	v_xor_b32_e32 v5, v24, v39
	v_ldexp_f32 v2, v2, v3
	v_mul_f32_e32 v2, v2, v37
	v_mul_f32_e32 v92, 0x3fb8aa3b, v2
	v_sub_u32_e32 v13, v13, v72
	v_lshlrev_b32_e32 v5, 4, v5
	v_add_u32_e32 v106, 0xffffff1f, v13
	v_lshlrev_b32_e32 v13, 8, v33
	v_lshlrev_b32_e32 v14, 8, v32
	v_or_b32_e32 v102, 31, v40
	v_add_u32_e32 v103, 0xffffff80, v40
	s_waitcnt vmcnt(2)
	v_add_f32_e32 v0, v0, v1
	v_mul_f32_e32 v0, v0, v20
	v_mul_f32_e32 v1, 0x4f800000, v0
	v_cmp_gt_f32_e32 vcc, s74, v0
	v_lshlrev_b32_e32 v40, 7, v101
	v_and_b32_e32 v5, 0x70, v5
	v_cndmask_b32_e32 v0, v0, v1, vcc
	v_sqrt_f32_e32 v1, v0
	v_sub_u32_e32 v13, v13, v14
	v_mov_b32_e32 v16, v73
	v_mov_b32_e32 v17, v73
	v_add_u32_e32 v2, -1, v1
	v_add_u32_e32 v3, 1, v1
	v_fma_f32 v6, -v2, v1, v0
	v_fma_f32 v7, -v3, v1, v0
	v_cmp_ge_f32_e64 s[0:1], 0, v6
	v_lshlrev_b32_e32 v6, 2, v38
	v_bitop3_b32 v6, v6, v23, 4 bitop3:0x6c
	v_cndmask_b32_e64 v1, v1, v2, s[0:1]
	v_cmp_lt_f32_e64 s[0:1], 0, v7
	v_lshlrev_b32_e32 v6, 4, v6
	v_or_b32_e32 v107, 0xdf, v13
	v_cndmask_b32_e64 v1, v1, v3, s[0:1]
	v_lshlrev_b32_e32 v3, 10, v38
	v_or3_b32 v3, v3, v6, v21
	v_or_b32_e32 v6, 2, v4
	v_lshlrev_b32_e32 v7, 7, v6
	v_lshrrev_b32_e32 v6, 1, v6
	v_bitop3_b32 v6, v6, v23, 5 bitop3:0x6c
	v_lshlrev_b32_e32 v6, 4, v6
	v_or3_b32 v6, v7, v6, v21
	v_or_b32_e32 v7, 3, v4
	v_lshlrev_b32_e32 v8, 7, v7
	v_lshrrev_b32_e32 v7, 1, v7
	v_bitop3_b32 v7, v7, v23, 5 bitop3:0x6c
	v_lshlrev_b32_e32 v7, 4, v7
	v_or3_b32 v7, v8, v7, v21
	v_or_b32_e32 v8, 4, v4
	v_lshlrev_b32_e32 v9, 7, v8
	v_lshrrev_b32_e32 v8, 1, v8
	v_bitop3_b32 v8, v8, v23, 6 bitop3:0x6c
	v_lshlrev_b32_e32 v8, 4, v8
	v_or3_b32 v8, v9, v8, v21
	v_or_b32_e32 v9, 5, v4
	v_lshlrev_b32_e32 v10, 7, v9
	v_lshrrev_b32_e32 v9, 1, v9
	v_bitop3_b32 v9, v9, v23, 6 bitop3:0x6c
	v_lshlrev_b32_e32 v9, 4, v9
	v_or3_b32 v9, v10, v9, v21
	v_or_b32_e32 v10, 6, v4
	v_mul_f32_e32 v2, 0x37800000, v1
	v_lshlrev_b32_e32 v11, 7, v10
	v_lshrrev_b32_e32 v10, 1, v10
	v_cndmask_b32_e32 v1, v1, v2, vcc
	v_cmp_class_f32_e32 vcc, v0, v94
	v_bitop3_b32 v10, v10, v23, 7 bitop3:0x6c
	v_lshlrev_b32_e32 v10, 4, v10
	v_cndmask_b32_e32 v0, v1, v0, vcc
	v_or_b32_e32 v4, 7, v4
	v_fmamk_f32 v0, v0, 0x3f8147ae, v95
	v_or3_b32 v10, v11, v10, v21
	v_lshlrev_b32_e32 v11, 7, v4
	v_lshrrev_b32_e32 v4, 1, v4
	v_add_f32_e32 v0, 0xc2700000, v0
	v_bitop3_b32 v4, v4, v23, 7 bitop3:0x6c
	v_max_f32_e32 v105, 0, v0
	v_lshrrev_b32_e32 v0, 1, v39
	v_bfe_u32 v1, v39, 1, 3
	v_lshlrev_b32_e32 v4, 4, v4
	v_or3_b32 v4, v11, v4, v21
	v_bitop3_b32 v0, v36, v0, 7 bitop3:0x78
	v_bitop3_b32 v11, v36, v1, 2 bitop3:0x36
	v_bitop3_b32 v12, v36, v1, 4 bitop3:0x36
	v_bitop3_b32 v1, v36, v1, 6 bitop3:0x36
	v_lshlrev_b32_e32 v2, 7, v34
	v_lshlrev_b32_e32 v0, 4, v0
	v_lshlrev_b32_e32 v11, 4, v11
	v_lshlrev_b32_e32 v12, 4, v12
	v_lshlrev_b32_e32 v1, 4, v1
	v_mov_b32_e32 v18, v73
	v_mov_b32_e32 v19, v73
	v_mov_b32_e32 v20, v73
	v_mov_b32_e32 v21, v73
	v_mov_b32_e32 v22, v73
	v_mov_b32_e32 v23, v73
	v_mov_b32_e32 v24, v73
	v_mov_b32_e32 v25, v73
	v_mov_b32_e32 v26, v73
	v_mov_b32_e32 v27, v73
	v_mov_b32_e32 v28, v73
	v_mov_b32_e32 v29, v73
	v_mov_b32_e32 v30, v73
	v_mov_b32_e32 v31, v73
	v_add_u32_e32 v108, v5, v40
	v_add_u32_e32 v109, v3, v41
	v_add_u32_e32 v110, v6, v41
	v_add_u32_e32 v111, v7, v41
	v_add_u32_e32 v112, v8, v41
	v_add_u32_e32 v113, v9, v41
	v_add_u32_e32 v114, v10, v41
	v_add_u32_e32 v115, v4, v41
	v_add_u32_e32 v116, v2, v0
	v_add_u32_e32 v117, v2, v11
	v_add_u32_e32 v118, v2, v12
	v_add_u32_e32 v119, v2, v1
	v_mov_b64_e32 v[0:1], v[16:17]
	v_mov_b32_e32 v93, v92
	v_mov_b32_e32 v104, 0
	s_mov_b64 s[66:67], 0
	v_mov_b64_e32 v[2:3], v[18:19]
	v_mov_b64_e32 v[4:5], v[20:21]
	v_mov_b64_e32 v[6:7], v[22:23]
	v_mov_b64_e32 v[8:9], v[24:25]
	v_mov_b64_e32 v[10:11], v[26:27]
	v_mov_b64_e32 v[12:13], v[28:29]
	v_mov_b64_e32 v[14:15], v[30:31]
	s_branch .LBB0_256

; template <int TYPE>
; DI void attn_item(const Params& p, int layer, int head, int qt, int dil, int res, int chunk, char* smem) {
;     ...
;   const int Q0 = qt * 256;
;   const int wq0 = Q0 + 32 * wid;
;   const int Uq = wq0 + ql;
;   const size_t tq = (size_t)Uq * dil + res;
;   bf16x8 qf[4];
; #pragma unroll
;   for (int ks = 0; ks < 4; ++ks) qf[ks] = *(const bf16x8*)(proj + tq * DIN + qcol + ks * 16 + h * 8);
;   char* sK = smem;
;   char* sV = smem + 8192;
;   volatile int* sflag = (volatile int*)(smem + FLG + 32);
;   volatile float* dred = (volatile float*)(smem + FLG + 96);
;   float slope = 0.f;
;   if (TYPE == 0) slope = exp2f(-8.f * (float)(head + 1) / 6.f) * (float)dil * LOG2E;
;   if (TYPE == 1) slope = exp2f(-2.f * (float)(head + 1)) * LOG2E;
;   const int wlim = (TYPE == 0) ? 128 : 0x3fffffff;
;   int kt_hi = (Q0 >> 6) + 3;
;   int kt_lo = 0;
;   float cref = 0.f;
;   if (TYPE == 0) {
;     kt_lo = (Q0 >> 6) - 2;
;     if (kt_lo < 0) kt_lo = 0;
;     const float* kma = (const float*)(p.ws + OFF_KMAX) + layer * 32;
;     const float km2 = kma[2 * head] + kma[2 * head + 1];
;     float qn2 = dot8(qf[0], qf[0]) + dot8(qf[1], qf[1]) + dot8(qf[2], qf[2]) + dot8(qf[3], qf[3]);
;     qn2 += __shfl_xor(qn2, 32);
;     const float R = sqrtf(qn2 * km2) * 1.01f + 0.01f;
;     cref = fmaxf(0.f, R - 60.f);
; DI void attn_phase(const Params& p, int layer, char* smem) {
;     ...
;   for (;;) {
;     __syncthreads();
;     if (threadIdx.x == 0) *s_item = atomicAdd(counter + 2, 1);
;     __syncthreads();
;     const int j = *s_item;
;     if (j >= 1152) break;
;     const int head = j % 6, branch = (j / 6) % 3, n = j / 18;
;     const int dil = branch == 0 ? 1 : branch == 1 ? 4 : 16;
;     attn_item<0>(p, layer, head, n / dil, dil, n % dil, branch, smem);
.LBB0_628:
	s_or_b64 exec, exec, s[0:1]
	s_waitcnt lgkmcnt(0)
	s_barrier
	ds_read_b32 v0, v76
	s_waitcnt lgkmcnt(0)
	s_mov_b64 s[0:1], -1
	s_waitcnt lgkmcnt(0)
	v_cmp_gt_i32_e32 vcc, s58, v0
	s_and_saveexec_b64 s[52:53], vcc
	s_cbranch_execz .LBB0_623
	v_mul_hi_i32 v1, v0, s59
	v_lshrrev_b32_e32 v2, 31, v1
	v_add_u32_e32 v1, v1, v2
	v_mul_lo_u32 v2, v1, 6
	v_sub_u32_e32 v78, v0, v2
	v_mul_hi_i32 v2, v1, s60
	v_lshrrev_b32_e32 v3, 31, v2
	v_add_u32_e32 v2, v2, v3
	v_lshl_add_u32 v2, v2, 1, v2
	v_sub_u32_e32 v80, v1, v2
	v_cmp_eq_u32_e32 vcc, 1, v80
	v_cmp_eq_u32_e64 s[0:1], 0, v80
	v_mul_hi_i32 v0, v0, s61
	v_cndmask_b32_e64 v2, 16, 4, vcc
	v_cndmask_b32_e64 v2, v2, 1, s[0:1]
	v_cvt_f32_ubyte0_e32 v37, v2
	v_rcp_iflag_f32_e32 v3, v37
	v_lshrrev_b32_e32 v1, 31, v0
	v_ashrrev_i32_e32 v0, 2, v0
	v_add_u32_e32 v0, v0, v1
	v_mul_f32_e32 v1, 0x4f7ffffe, v3
	v_cvt_u32_f32_e32 v1, v1
	v_sub_u32_e32 v4, 0, v2
	v_sub_u32_e32 v3, 0, v0
	v_max_i32_e32 v3, v0, v3
	v_mul_lo_u32 v4, v4, v1
	v_mul_hi_u32 v4, v1, v4
	v_add_u32_e32 v1, v1, v4
	v_mul_hi_u32 v1, v3, v1
	v_mul_lo_u32 v4, v1, v2
	v_sub_u32_e32 v3, v3, v4
	v_add_u32_e32 v4, 1, v1
	v_cmp_ge_u32_e64 s[2:3], v3, v2
	v_ashrrev_i32_e32 v32, 31, v0
	v_mov_b32_e32 v39, v158
	v_cndmask_b32_e64 v1, v1, v4, s[2:3]
	v_sub_u32_e32 v4, v3, v2
	v_cndmask_b32_e64 v3, v3, v4, s[2:3]
	v_add_u32_e32 v4, 1, v1
	v_cmp_ge_u32_e64 s[2:3], v3, v2
	v_lshlrev_b32_e32 v84, 6, v78
	v_ashrrev_i32_e32 v38, 6, v39
	v_cndmask_b32_e64 v1, v1, v4, s[2:3]
	v_xor_b32_e32 v33, v1, v32
	v_sub_u32_e32 v3, v33, v32
	v_lshlrev_b32_e32 v35, 5, v38
	v_mul_lo_u32 v1, v3, v2
	v_and_b32_e32 v34, 31, v39
	v_lshl_add_u32 v40, v3, 8, v35
	v_sub_u32_e32 v86, v0, v1
	v_or_b32_e32 v0, v40, v34
	v_cndmask_b32_e64 v2, 4, 2, vcc
	v_ashrrev_i32_e32 v1, 31, v0
	v_cndmask_b32_e64 v79, v2, 0, s[0:1]
	v_lshlrev_b64 v[0:1], v79, v[0:1]
	v_ashrrev_i32_e32 v87, 31, v86
	v_lshl_add_u64 v[82:83], v[0:1], 0, v[86:87]
	v_mov_b64_e32 v[0:1], s[12:13]
	v_mad_u64_u32 v[0:1], s[0:1], v82, s62, v[0:1]
	v_bfe_u32 v36, v39, 5, 1
	v_mad_i32_i24 v1, v83, s62, v1
	v_ashrrev_i32_e32 v85, 31, v84
	v_lshl_add_u64 v[0:1], v[84:85], 1, v[0:1]
	v_lshlrev_b32_e32 v72, 4, v36
	v_lshl_add_u64 v[0:1], v[0:1], 0, v[72:73]
	global_load_dwordx4 v[48:51], v[0:1], off
	global_load_dwordx4 v[52:55], v[0:1], off offset:32
	global_load_dwordx4 v[56:59], v[0:1], off offset:64
	global_load_dwordx4 v[60:63], v[0:1], off offset:96
	v_mov_b32_e32 v171, v3
	v_mov_b32_e32 v195, v73
	v_lshlrev_b32_e32 v168, 2, v171
	v_or_b32_e32 v197, 3, v168
	v_and_b32_e32 v196, 63, v39
	v_lshlrev_b32_e32 v168, 1, v78
	v_ashrrev_i32_e32 v169, 31, v168
	v_lshl_add_u64 v[168:169], v[168:169], 2, s[34:35]
	global_load_dwordx2 v[168:169], v[168:169], off
	v_add_u32_e32 v194, 0x180, v84
	v_ashrrev_i32_e32 v198, 3, v39
	v_lshlrev_b32_e32 v174, 4, v39
	v_lshlrev_b32_e32 v180, 6, v197
	v_mov_b32_e32 v175, v195
	v_lshlrev_b64 v[178:179], 1, v[194:195]
	v_and_b32_e32 v194, 0x70, v174
	v_or_b32_e32 v174, v196, v180
	v_add_u32_e32 v180, v198, v180
	v_lshlrev_b64 v[174:175], v79, v[174:175]
	v_ashrrev_i32_e32 v181, 31, v180
	v_mov_b64_e32 v[176:177], s[12:13]
	v_lshl_add_u64 v[174:175], v[174:175], 0, v[86:87]
	v_lshlrev_b64 v[180:181], v79, v[180:181]
	v_add_u32_e32 v170, 0x300, v84
	v_mov_b32_e32 v171, v195
	v_lshlrev_b32_e32 v172, 3, v38
	v_mad_u64_u32 v[182:183], s[98:99], v174, s62, v[176:177]
	v_lshl_add_u64 v[180:181], v[180:181], 0, v[86:87]
	v_ashrrev_i32_e32 v173, 31, v172
	v_lshlrev_b64 v[170:171], 1, v[170:171]
	v_mad_i32_i24 v183, v175, s62, v183
	v_mad_u64_u32 v[174:175], s[98:99], v180, s62, v[176:177]
	v_lshlrev_b64 v[184:185], 1, v[172:173]
	v_lshl_add_u64 v[170:171], v[182:183], 0, v[170:171]
	v_mad_i32_i24 v175, v181, s62, v175
	v_lshl_add_u64 v[170:171], v[170:171], 0, v[184:185]
	v_lshl_add_u64 v[174:175], v[174:175], 0, v[178:179]
	global_load_dwordx4 v[186:189], v[170:171], off
	v_lshl_add_u64 v[170:171], v[174:175], 0, v[194:195]
	global_load_dwordx4 v[190:193], v[170:171], off
	v_lshlrev_b32_e32 v0, 2, v3
	v_max_i32_e32 v1, 2, v0
	v_or_b32_e32 v81, 3, v0
	v_add_u32_e32 v99, -2, v1
	v_and_b32_e32 v75, 63, v39
	v_cmp_ge_i32_e32 vcc, v81, v99
	v_lshlrev_b32_e32 v72, 2, v36
	s_waitcnt vmcnt(6)
	v_and_b32_e32 v3, 0xffff0000, v48
	s_waitcnt vmcnt(5)
	v_and_b32_e32 v11, 0xffff0000, v52
	v_lshlrev_b32_e32 v2, 16, v48
	v_lshlrev_b32_e32 v10, 16, v52
	v_mul_f32_e32 v3, v3, v3
	v_mul_f32_e32 v11, v11, v11
	v_lshlrev_b32_e32 v4, 16, v49
	v_lshlrev_b32_e32 v12, 16, v53
	v_fmac_f32_e32 v3, v2, v2
	v_fmac_f32_e32 v11, v10, v10
	v_and_b32_e32 v5, 0xffff0000, v49
	v_and_b32_e32 v13, 0xffff0000, v53
	v_fmac_f32_e32 v3, v4, v4
	v_fmac_f32_e32 v11, v12, v12
	v_lshlrev_b32_e32 v6, 16, v50
	v_lshlrev_b32_e32 v14, 16, v54
	s_waitcnt vmcnt(4)
	v_and_b32_e32 v19, 0xffff0000, v56
	v_fmac_f32_e32 v3, v5, v5
	v_fmac_f32_e32 v11, v13, v13
	v_and_b32_e32 v7, 0xffff0000, v50
	v_and_b32_e32 v15, 0xffff0000, v54
	v_lshlrev_b32_e32 v18, 16, v56
	s_waitcnt vmcnt(3)
	v_and_b32_e32 v27, 0xffff0000, v60
	v_mul_f32_e32 v19, v19, v19
	v_fmac_f32_e32 v3, v6, v6
	v_fmac_f32_e32 v11, v14, v14
	v_lshlrev_b32_e32 v8, 16, v51
	v_lshlrev_b32_e32 v16, 16, v55
	v_lshlrev_b32_e32 v20, 16, v57
	v_lshlrev_b32_e32 v26, 16, v60
	v_mul_f32_e32 v27, v27, v27
	v_fmac_f32_e32 v19, v18, v18
	v_fmac_f32_e32 v3, v7, v7
	v_fmac_f32_e32 v11, v15, v15
	v_and_b32_e32 v9, 0xffff0000, v51
	v_and_b32_e32 v17, 0xffff0000, v55
	v_and_b32_e32 v21, 0xffff0000, v57
	v_lshlrev_b32_e32 v28, 16, v61
	v_fmac_f32_e32 v27, v26, v26
	v_fmac_f32_e32 v19, v20, v20
	v_fmac_f32_e32 v3, v8, v8
	v_fmac_f32_e32 v11, v16, v16
	v_lshlrev_b32_e32 v22, 16, v58
	v_and_b32_e32 v29, 0xffff0000, v61
	v_fmac_f32_e32 v27, v28, v28
	v_fmac_f32_e32 v19, v21, v21
	v_fmac_f32_e32 v3, v9, v9
	v_fmac_f32_e32 v11, v17, v17
	v_and_b32_e32 v23, 0xffff0000, v58
	v_fmac_f32_e32 v19, v22, v22
	v_add_f32_e32 v2, v3, v11
	v_fmac_f32_e32 v27, v29, v29
	v_lshlrev_b32_e32 v3, 16, v62
	v_lshlrev_b32_e32 v24, 16, v59
	v_fmac_f32_e32 v19, v23, v23
	v_fmac_f32_e32 v27, v3, v3
	v_and_b32_e32 v3, 0xffff0000, v62
	v_and_b32_e32 v25, 0xffff0000, v59
	v_fmac_f32_e32 v19, v24, v24
	v_fmac_f32_e32 v27, v3, v3
	v_lshlrev_b32_e32 v3, 16, v63
	v_fmac_f32_e32 v19, v25, v25
	v_fmac_f32_e32 v27, v3, v3
	v_and_b32_e32 v3, 0xffff0000, v63
	v_add_f32_e32 v2, v2, v19
	v_fmac_f32_e32 v27, v3, v3
	v_add_f32_e32 v41, v2, v27
	ds_bpermute_b32 v42, v159, v41
	s_and_saveexec_b64 s[0:1], vcc
	s_xor_b64 s[54:55], exec, s[0:1]
	s_cbranch_execz .LBB0_637
; template <int TYPE>
; DI void attn_item(const Params& p, int layer, int head, int qt, int dil, int res, int chunk, char* smem) {
;     ...
;   if (TYPE == 0) slope = exp2f(-8.f * (float)(head + 1) / 6.f) * (float)dil * LOG2E;
;   if (TYPE == 1) slope = exp2f(-2.f * (float)(head + 1)) * LOG2E;
;   const int wlim = (TYPE == 0) ? 128 : 0x3fffffff;
;   int kt_hi = (Q0 >> 6) + 3;
;   int kt_lo = 0;
;   float cref = 0.f;
;   if (TYPE == 0) {
;     kt_lo = (Q0 >> 6) - 2;
;     if (kt_lo < 0) kt_lo = 0;
;     const float* kma = (const float*)(p.ws + OFF_KMAX) + layer * 32;
;     const float km2 = kma[2 * head] + kma[2 * head + 1];
;     float qn2 = dot8(qf[0], qf[0]) + dot8(qf[1], qf[1]) + dot8(qf[2], qf[2]) + dot8(qf[3], qf[3]);
;     qn2 += __shfl_xor(qn2, 32);
;     const float R = sqrtf(qn2 * km2) * 1.01f + 0.01f;
;     cref = fmaxf(0.f, R - 60.f);
;     ...
;   float l1 = 0.f, l2 = 0.f, carry = 0.f;
;   f32x16 O1a, O1b, O2a, O2b;
; #pragma unroll
;   for (int i = 0; i < 16; ++i) { O1a[i] = 0.f; O1b[i] = 0.f; O2a[i] = 0.f; O2b[i] = 0.f; }
;   bf16x8 Tm0, Tm1;
;   if (TYPE == 2) {
; #pragma unroll
;     for (int jj = 0; jj < 8; ++jj) {
;       int k0 = 8 * (jj >> 2) + 4 * h + (jj & 3);
;       Tm0[jj] = (k0 > ql) ? (short)0x3F80 : (short)0;
;       Tm1[jj] = (16 + k0 > ql) ? (short)0x3F80 : (short)0;
;     }
;     if (tid < 8) sflag[tid] = 0;
;   }
;   const int kkey0 = tid >> 3, kchunk = tid & 7;
;   const int vkey = tid & 63, vdc0 = tid >> 6;
;   const int vk5 = vkey & 31;
;   const int vpos = (vkey & 32) | (vk5 & 0x13) | ((vk5 & 8) >> 1) | ((vk5 & 4) << 1);
;   uint4 kreg0, vreg0;
;     ...
;   ATT_PREFETCH((kt_hi >= kt_lo) ? kt_hi : 0);
	v_lshlrev_b32_e32 v0, 1, v78
	v_ashrrev_i32_e32 v1, 31, v0
	v_lshl_add_u64 v[0:1], v[0:1], 2, s[34:35]
	s_waitcnt vmcnt(2)
	v_mov_b64_e32 v[0:1], v[168:169]
	v_add_u32_e32 v72, 0x180, v84
	v_ashrrev_i32_e32 v100, 3, v39
	v_lshlrev_b32_e32 v6, 4, v39
	v_lshlrev_b32_e32 v12, 6, v81
	v_mov_b32_e32 v7, v73
	v_lshlrev_b32_e32 v13, 1, v39
	v_and_b32_e32 v14, 48, v39
	v_lshlrev_b64 v[10:11], 1, v[72:73]
	v_and_b32_e32 v72, 0x70, v6
	v_or_b32_e32 v6, v75, v12
	v_add_u32_e32 v12, v100, v12
	s_waitcnt lgkmcnt(0)
	v_add_f32_e32 v20, v41, v42
	v_and_or_b32 v23, v13, 8, v14
	v_and_b32_e32 v41, 6, v13
	v_lshlrev_b64 v[6:7], v79, v[6:7]
	v_ashrrev_i32_e32 v13, 31, v12
	v_mov_b64_e32 v[8:9], s[12:13]
	v_lshl_add_u64 v[14:15], s[12:13], 0, v[10:11]
	v_lshl_add_u64 v[6:7], v[6:7], 0, v[86:87]
	v_lshlrev_b64 v[12:13], v79, v[12:13]
	v_add_u32_e32 v5, 1, v78
	v_add_u32_e32 v2, 0x300, v84
	v_mov_b32_e32 v3, v73
	v_lshlrev_b32_e32 v4, 3, v38
	v_lshl_add_u64 v[88:89], v[14:15], 0, v[72:73]
	v_mad_u64_u32 v[14:15], s[0:1], v6, s62, v[8:9]
	v_lshl_add_u64 v[12:13], v[12:13], 0, v[86:87]
	v_cvt_f32_i32_e32 v22, v5
	v_ashrrev_i32_e32 v5, 31, v4
	v_lshlrev_b64 v[2:3], 1, v[2:3]
	v_mad_i32_i24 v15, v7, s62, v15
	v_mad_u64_u32 v[6:7], s[0:1], v12, s62, v[8:9]
	v_lshl_add_u64 v[16:17], s[12:13], 0, v[2:3]
	v_lshlrev_b64 v[18:19], 1, v[4:5]
	v_lshl_add_u64 v[2:3], v[14:15], 0, v[2:3]
	v_mad_i32_i24 v7, v13, s62, v7
	v_lshl_add_u64 v[2:3], v[2:3], 0, v[18:19]
	v_lshl_add_u64 v[6:7], v[6:7], 0, v[10:11]
	s_waitcnt vmcnt(0)
	v_mov_b64_e32 v[64:65], v[186:187]
	v_mov_b64_e32 v[66:67], v[188:189]
	v_lshl_add_u64 v[2:3], v[6:7], 0, v[72:73]
	v_mov_b64_e32 v[68:69], v[190:191]
	v_mov_b64_e32 v[70:71], v[192:193]
	v_lshl_add_u64 v[90:91], v[16:17], 0, v[18:19]
	v_mul_f32_e32 v16, 0xc1000000, v22
	v_div_scale_f32 v8, s[0:1], s63, s63, v16
	v_rcp_f32_e32 v12, v8
	v_div_scale_f32 v9, vcc, v16, s63, v16
	v_lshrrev_b32_e32 v23, 3, v23
	v_fma_f32 v2, -v8, v12, 1.0
	v_fmac_f32_e32 v12, v2, v12
	v_mul_f32_e32 v2, v9, v12
	v_fma_f32 v3, -v8, v2, v9
	v_fmac_f32_e32 v2, v3, v12
	v_fma_f32 v3, -v8, v2, v9
	v_div_fmas_f32 v2, v3, v12, v2
	v_div_fixup_f32 v2, v2, s63, v16
	v_cmp_gt_f32_e32 vcc, s64, v2
	v_and_b32_e32 v21, 8, v39
	v_lshrrev_b32_e32 v24, 1, v100
	v_cndmask_b32_e32 v3, 0, v96, vcc
	v_add_f32_e32 v2, v2, v3
	v_cndmask_b32_e32 v3, 0, v97, vcc
	v_exp_f32_e32 v2, v2
	v_lshlrev_b32_e32 v72, 2, v36
	v_add_u32_e32 v13, v35, v34
	v_xor_b32_e32 v5, v24, v39
	v_ldexp_f32 v2, v2, v3
	v_mul_f32_e32 v2, v2, v37
	v_mul_f32_e32 v92, 0x3fb8aa3b, v2
	v_sub_u32_e32 v13, v13, v72
	v_lshlrev_b32_e32 v5, 4, v5
	v_add_u32_e32 v105, 0xffffff1f, v13
	v_lshlrev_b32_e32 v13, 8, v33
	v_lshlrev_b32_e32 v14, 8, v32
	v_or_b32_e32 v101, 31, v40
	v_add_u32_e32 v102, 0xffffff80, v40
	s_waitcnt vmcnt(2)
	v_add_f32_e32 v0, v0, v1
	v_mul_f32_e32 v0, v0, v20
	v_mul_f32_e32 v1, 0x4f800000, v0
	v_cmp_gt_f32_e32 vcc, s65, v0
	v_lshlrev_b32_e32 v40, 7, v100
	v_and_b32_e32 v5, 0x70, v5
	v_cndmask_b32_e32 v0, v0, v1, vcc
	v_sqrt_f32_e32 v1, v0
	v_sub_u32_e32 v13, v13, v14
	v_mov_b32_e32 v16, v73
	v_mov_b32_e32 v17, v73
	v_add_u32_e32 v2, -1, v1
	v_add_u32_e32 v3, 1, v1
	v_fma_f32 v6, -v2, v1, v0
	v_fma_f32 v7, -v3, v1, v0
	v_cmp_ge_f32_e64 s[0:1], 0, v6
	v_lshlrev_b32_e32 v6, 2, v38
	v_bitop3_b32 v6, v6, v23, 4 bitop3:0x6c
	v_cndmask_b32_e64 v1, v1, v2, s[0:1]
	v_cmp_lt_f32_e64 s[0:1], 0, v7
	v_lshlrev_b32_e32 v6, 4, v6
	v_or_b32_e32 v106, 0xdf, v13
	v_cndmask_b32_e64 v1, v1, v3, s[0:1]
	v_lshlrev_b32_e32 v3, 10, v38
	v_or3_b32 v3, v3, v6, v21
	v_or_b32_e32 v6, 2, v4
	v_lshlrev_b32_e32 v7, 7, v6
	v_lshrrev_b32_e32 v6, 1, v6
	v_bitop3_b32 v6, v6, v23, 5 bitop3:0x6c
	v_lshlrev_b32_e32 v6, 4, v6
	v_or3_b32 v6, v7, v6, v21
	v_or_b32_e32 v7, 3, v4
	v_lshlrev_b32_e32 v8, 7, v7
	v_lshrrev_b32_e32 v7, 1, v7
	v_bitop3_b32 v7, v7, v23, 5 bitop3:0x6c
	v_lshlrev_b32_e32 v7, 4, v7
	v_or3_b32 v7, v8, v7, v21
	v_or_b32_e32 v8, 4, v4
	v_lshlrev_b32_e32 v9, 7, v8
	v_lshrrev_b32_e32 v8, 1, v8
	v_bitop3_b32 v8, v8, v23, 6 bitop3:0x6c
	v_lshlrev_b32_e32 v8, 4, v8
	v_or3_b32 v8, v9, v8, v21
	v_or_b32_e32 v9, 5, v4
	v_lshlrev_b32_e32 v10, 7, v9
	v_lshrrev_b32_e32 v9, 1, v9
	v_bitop3_b32 v9, v9, v23, 6 bitop3:0x6c
	v_lshlrev_b32_e32 v9, 4, v9
	v_or3_b32 v9, v10, v9, v21
	v_or_b32_e32 v10, 6, v4
	v_mul_f32_e32 v2, 0x37800000, v1
	v_lshlrev_b32_e32 v11, 7, v10
	v_lshrrev_b32_e32 v10, 1, v10
	v_cndmask_b32_e32 v1, v1, v2, vcc
	v_cmp_class_f32_e32 vcc, v0, v94
	v_bitop3_b32 v10, v10, v23, 7 bitop3:0x6c
	v_lshlrev_b32_e32 v10, 4, v10
	v_cndmask_b32_e32 v0, v1, v0, vcc
	v_or_b32_e32 v4, 7, v4
	v_fmamk_f32 v0, v0, 0x3f8147ae, v95
	v_or3_b32 v10, v11, v10, v21
	v_lshlrev_b32_e32 v11, 7, v4
	v_lshrrev_b32_e32 v4, 1, v4
	v_add_f32_e32 v0, 0xc2700000, v0
	v_bitop3_b32 v4, v4, v23, 7 bitop3:0x6c
	v_max_f32_e32 v104, 0, v0
	v_lshrrev_b32_e32 v0, 1, v39
	v_bfe_u32 v1, v39, 1, 3
	v_lshlrev_b32_e32 v4, 4, v4
	v_or3_b32 v4, v11, v4, v21
	v_bitop3_b32 v0, v36, v0, 7 bitop3:0x78
	v_bitop3_b32 v11, v36, v1, 2 bitop3:0x36
	v_bitop3_b32 v12, v36, v1, 4 bitop3:0x36
	v_bitop3_b32 v1, v36, v1, 6 bitop3:0x36
	v_lshlrev_b32_e32 v2, 7, v34
	v_lshlrev_b32_e32 v0, 4, v0
	v_lshlrev_b32_e32 v11, 4, v11
	v_lshlrev_b32_e32 v12, 4, v12
	v_lshlrev_b32_e32 v1, 4, v1
	v_mov_b32_e32 v18, v73
	v_mov_b32_e32 v19, v73
	v_mov_b32_e32 v20, v73
	v_mov_b32_e32 v21, v73
	v_mov_b32_e32 v22, v73
	v_mov_b32_e32 v23, v73
	v_mov_b32_e32 v24, v73
	v_mov_b32_e32 v25, v73
	v_mov_b32_e32 v26, v73
	v_mov_b32_e32 v27, v73
	v_mov_b32_e32 v28, v73
	v_mov_b32_e32 v29, v73
	v_mov_b32_e32 v30, v73
	v_mov_b32_e32 v31, v73
	v_add_u32_e32 v107, v5, v40
	v_add_u32_e32 v108, v3, v41
	v_add_u32_e32 v109, v6, v41
	v_add_u32_e32 v110, v7, v41
	v_add_u32_e32 v111, v8, v41
	v_add_u32_e32 v112, v9, v41
	v_add_u32_e32 v113, v10, v41
	v_add_u32_e32 v114, v4, v41
	v_add_u32_e32 v115, v2, v0
	v_add_u32_e32 v116, v2, v11
	v_add_u32_e32 v117, v2, v12
	v_add_u32_e32 v118, v2, v1
	v_mov_b64_e32 v[0:1], v[16:17]
	v_mov_b32_e32 v93, v92
	v_mov_b32_e32 v103, 0
	s_mov_b64 s[56:57], 0
	v_mov_b64_e32 v[2:3], v[18:19]
	v_mov_b64_e32 v[4:5], v[20:21]
	v_mov_b64_e32 v[6:7], v[22:23]
	v_mov_b64_e32 v[8:9], v[24:25]
	v_mov_b64_e32 v[10:11], v[26:27]
	v_mov_b64_e32 v[12:13], v[28:29]
	v_mov_b64_e32 v[14:15], v[30:31]
	s_branch .LBB0_632
